# speedup vs baseline: 1.0026x; 1.0026x over previous
.LBB0_60:
	s_or_b64 exec, exec, s[8:9]
	s_and_saveexec_b64 s[4:5], s[10:11]
	s_cbranch_execz .LBB0_62
	global_atomic_add v[2:3], v207, off
	s_and_b64 s[30:31], s[28:29], exec
	s_cbranch_scc0 .Lbar_nobc
	s_add_u32 s30, s24, 0x2800
	s_addc_u32 s31, s25, 0
	global_atomic_add v0, v207, s[30:31] offset:-1024
	global_atomic_add v0, v207, s[30:31] offset:-768
	global_atomic_add v0, v207, s[30:31] offset:-512
	global_atomic_add v0, v207, s[30:31] offset:-256
	global_atomic_add v0, v207, s[30:31] offset:0
	global_atomic_add v0, v207, s[30:31] offset:256
	global_atomic_add v0, v207, s[30:31] offset:512
	global_atomic_add v0, v207, s[30:31] offset:768
	global_atomic_add v0, v207, s[30:31] offset:1024
	global_atomic_add v0, v207, s[30:31] offset:1280
	global_atomic_add v0, v207, s[30:31] offset:1536
	global_atomic_add v0, v207, s[30:31] offset:1792
	global_atomic_add v0, v207, s[30:31] offset:2048
	global_atomic_add v0, v207, s[30:31] offset:2304
	global_atomic_add v0, v207, s[30:31] offset:2560
	global_atomic_add v0, v207, s[30:31] offset:2816
